# attention-output GEMM gated epilogue de-serialised: all 16 gate tiles fetched up front into dead fragment registers (one round trip per unit instead of eight)
# baseline (speedup 1.0000x reference)
; __device__ __forceinline__ unsigned pk_bf16(float lo, float hi) { const f32x2 v = {lo, hi}; const bf16x2_t b = __builtin_convertvector(v, bf16x2_t); return __builtin_bit_cast(unsigned, b); }
; __device__ __forceinline__ float lo_bf(unsigned w) { return __uint_as_float(w << 16); }
; __device__ __forceinline__ float hi_bf(unsigned w) { return __uint_as_float(w & 0xffff0000u); }
;     __device__ __forceinline__ void operator()(const f32x4 (&acc)[2][2][4][2], const Unit& u, int wr, int wc, int fr, int fq) const {
;         const int row0 = u.pm * BM + wr * 64 + fr, col0 = u.pn * BM + wc * 32 + 8 * fq;
; #pragma unroll
;         for (int ai = 0; ai < 2; ++ai)
; #pragma unroll
;             for (int m = 0; m < 4; ++m) {
;                 const size_t off = (size_t)(row0 + ai * HALF + m * 16) * D + col0;
; #pragma unroll
;                 for (int bj = 0; bj < 2; ++bj) {
;                     const u32x4 gw = *(const u32x4*)(gate + off + bj * HALF);
;                     const f32x4 v0 = acc[ai][bj][m][0], v1 = acc[ai][bj][m][1];
;                     float r[8];
;                     r[0] = lo_bf(gw.x) * v0[0]; r[1] = hi_bf(gw.x) * v0[1]; r[2] = lo_bf(gw.y) * v0[2]; r[3] = hi_bf(gw.y) * v0[3];
;                     r[4] = lo_bf(gw.z) * v1[0]; r[5] = hi_bf(gw.z) * v1[1]; r[6] = lo_bf(gw.w) * v1[2]; r[7] = hi_bf(gw.w) * v1[3];
;                     if (ADD) {
;                         const u32x4 aw = *(const u32x4*)(add + off + bj * HALF);
;                         r[0] += lo_bf(aw.x); r[1] += hi_bf(aw.x); r[2] += lo_bf(aw.y); r[3] += hi_bf(aw.y);
;                         r[4] += lo_bf(aw.z); r[5] += hi_bf(aw.z); r[6] += lo_bf(aw.w); r[7] += hi_bf(aw.w);
;                     }
;                     u32x4 w; w.x = pk_bf16(r[0], r[1]); w.y = pk_bf16(r[2], r[3]); w.z = pk_bf16(r[4], r[5]); w.w = pk_bf16(r[6], r[7]);
;                     *(u32x4*)(out + off + bj * HALF) = w;
;                 }
;                 asm volatile("" ::: "memory");
;             }
.LBB0_875:
	s_lshl_b32 s30, s30, 8
	v_mbcnt_lo_u32_b32 v146, -1, 0
	v_mbcnt_hi_u32_b32 v146, -1, v146
	s_add_i32 s30, s30, s62
	v_and_or_b32 v148, v146, 15, s30
	s_lshl_b32 s30, s33, 8
	v_ashrrev_i32_e32 v146, 1, v146
	s_or_b32 s30, s30, s63
	v_and_b32_e32 v146, -8, v146
	v_add_u32_e32 v146, s30, v146
	v_ashrrev_i32_e32 v149, 31, v148
	v_ashrrev_i32_e32 v147, 31, v146
	v_lshlrev_b64 v[150:151], 11, v[148:149]
	v_lshl_add_u64 v[170:171], s[18:19], 0, v[150:151]
	v_lshlrev_b64 v[150:151], 1, v[146:147]
	v_lshl_add_u64 v[146:147], v[170:171], 0, v[150:151]
	v_lshl_add_u32 v149, v148, 11, v150
	s_mov_b64 s[78:79], s[18:19]
	s_add_u32 s80, s18, 0x8000
	s_addc_u32 s81, s19, 0
	s_add_u32 s82, s18, 0x10000
	s_addc_u32 s83, s19, 0
	s_add_u32 s84, s18, 0x18000
	s_addc_u32 s85, s19, 0
	s_add_u32 s86, s18, 0x40000
	s_addc_u32 s87, s19, 0
	s_add_u32 s88, s18, 0x48000
	s_addc_u32 s89, s19, 0
	s_add_u32 s68, s18, 0x50000
	s_addc_u32 s69, s19, 0
	s_add_u32 s70, s18, 0x58000
	s_addc_u32 s71, s19, 0
	global_load_dwordx4 v[170:173], v149, s[78:79]
	global_load_dwordx4 v[174:177], v149, s[78:79] offset:256
	global_load_dwordx4 v[178:181], v149, s[80:81]
	global_load_dwordx4 v[182:185], v149, s[80:81] offset:256
	global_load_dwordx4 v[186:189], v149, s[82:83]
	global_load_dwordx4 v[190:193], v149, s[82:83] offset:256
	global_load_dwordx4 v[194:197], v149, s[84:85]
	global_load_dwordx4 v[198:201], v149, s[84:85] offset:256
	global_load_dwordx4 v[202:205], v149, s[86:87]
	global_load_dwordx4 v[206:209], v149, s[86:87] offset:256
	global_load_dwordx4 v[210:213], v149, s[88:89]
	global_load_dwordx4 v[214:217], v149, s[88:89] offset:256
	global_load_dwordx4 v[218:221], v149, s[68:69]
	global_load_dwordx4 v[222:225], v149, s[68:69] offset:256
	global_load_dwordx4 v[226:229], v149, s[70:71]
	global_load_dwordx4 v[230:233], v149, s[70:71] offset:256
	s_waitcnt vmcnt(14)
	v_lshlrev_b32_e32 v234, 16, v170
	v_and_b32_e32 v235, 0xffff0000, v170
	v_lshlrev_b32_e32 v236, 16, v171
	v_and_b32_e32 v237, 0xffff0000, v171
	v_lshlrev_b32_e32 v238, 16, v172
	v_and_b32_e32 v239, 0xffff0000, v172
	v_lshlrev_b32_e32 v240, 16, v173
	v_and_b32_e32 v241, 0xffff0000, v173
	v_lshlrev_b32_e32 v242, 16, v174
	v_and_b32_e32 v243, 0xffff0000, v174
	v_lshlrev_b32_e32 v244, 16, v175
	v_and_b32_e32 v245, 0xffff0000, v175
	v_lshlrev_b32_e32 v246, 16, v176
	v_and_b32_e32 v247, 0xffff0000, v176
	v_lshlrev_b32_e32 v150, 16, v177
	v_and_b32_e32 v151, 0xffff0000, v177
	v_pk_mul_f32 v[124:125], v[124:125], v[234:235]
	v_pk_mul_f32 v[126:127], v[126:127], v[236:237]
	v_pk_mul_f32 v[120:121], v[120:121], v[238:239]
	v_pk_mul_f32 v[122:123], v[122:123], v[240:241]
	v_pk_mul_f32 v[116:117], v[116:117], v[242:243]
	v_pk_mul_f32 v[118:119], v[118:119], v[244:245]
	v_pk_mul_f32 v[112:113], v[112:113], v[246:247]
	v_pk_mul_f32 v[114:115], v[114:115], v[150:151]
	v_cvt_pk_bf16_f32 v170, v124, v125
	v_cvt_pk_bf16_f32 v171, v126, v127
	v_cvt_pk_bf16_f32 v172, v120, v121
	v_cvt_pk_bf16_f32 v173, v122, v123
	v_cvt_pk_bf16_f32 v174, v116, v117
	v_cvt_pk_bf16_f32 v175, v118, v119
	v_cvt_pk_bf16_f32 v176, v112, v113
	v_cvt_pk_bf16_f32 v177, v114, v115
	global_store_dwordx4 v149, v[170:173], s[78:79]
	global_store_dwordx4 v149, v[174:177], s[78:79] offset:256
	s_waitcnt vmcnt(14)
	v_lshlrev_b32_e32 v234, 16, v178
	v_and_b32_e32 v235, 0xffff0000, v178
	v_lshlrev_b32_e32 v236, 16, v179
	v_and_b32_e32 v237, 0xffff0000, v179
	v_lshlrev_b32_e32 v238, 16, v180
	v_and_b32_e32 v239, 0xffff0000, v180
	v_lshlrev_b32_e32 v240, 16, v181
	v_and_b32_e32 v241, 0xffff0000, v181
	v_lshlrev_b32_e32 v242, 16, v182
	v_and_b32_e32 v243, 0xffff0000, v182
	v_lshlrev_b32_e32 v244, 16, v183
	v_and_b32_e32 v245, 0xffff0000, v183
	v_lshlrev_b32_e32 v246, 16, v184
	v_and_b32_e32 v247, 0xffff0000, v184
	v_lshlrev_b32_e32 v150, 16, v185
	v_and_b32_e32 v151, 0xffff0000, v185
	v_pk_mul_f32 v[108:109], v[108:109], v[234:235]
	v_pk_mul_f32 v[110:111], v[110:111], v[236:237]
	v_pk_mul_f32 v[104:105], v[104:105], v[238:239]
	v_pk_mul_f32 v[106:107], v[106:107], v[240:241]
	v_pk_mul_f32 v[100:101], v[100:101], v[242:243]
	v_pk_mul_f32 v[102:103], v[102:103], v[244:245]
	v_pk_mul_f32 v[96:97], v[96:97], v[246:247]
	v_pk_mul_f32 v[98:99], v[98:99], v[150:151]
	v_cvt_pk_bf16_f32 v178, v108, v109
	v_cvt_pk_bf16_f32 v179, v110, v111
	v_cvt_pk_bf16_f32 v180, v104, v105
	v_cvt_pk_bf16_f32 v181, v106, v107
	v_cvt_pk_bf16_f32 v182, v100, v101
	v_cvt_pk_bf16_f32 v183, v102, v103
	v_cvt_pk_bf16_f32 v184, v96, v97
	v_cvt_pk_bf16_f32 v185, v98, v99
	global_store_dwordx4 v149, v[178:181], s[80:81]
	global_store_dwordx4 v149, v[182:185], s[80:81] offset:256
	s_waitcnt vmcnt(14)
	v_lshlrev_b32_e32 v234, 16, v186
	v_and_b32_e32 v235, 0xffff0000, v186
	v_lshlrev_b32_e32 v236, 16, v187
	v_and_b32_e32 v237, 0xffff0000, v187
	v_lshlrev_b32_e32 v238, 16, v188
	v_and_b32_e32 v239, 0xffff0000, v188
	v_lshlrev_b32_e32 v240, 16, v189
	v_and_b32_e32 v241, 0xffff0000, v189
	v_lshlrev_b32_e32 v242, 16, v190
	v_and_b32_e32 v243, 0xffff0000, v190
	v_lshlrev_b32_e32 v244, 16, v191
	v_and_b32_e32 v245, 0xffff0000, v191
	v_lshlrev_b32_e32 v246, 16, v192
	v_and_b32_e32 v247, 0xffff0000, v192
	v_lshlrev_b32_e32 v150, 16, v193
	v_and_b32_e32 v151, 0xffff0000, v193
	v_pk_mul_f32 v[92:93], v[92:93], v[234:235]
	v_pk_mul_f32 v[94:95], v[94:95], v[236:237]
	v_pk_mul_f32 v[88:89], v[88:89], v[238:239]
	v_pk_mul_f32 v[90:91], v[90:91], v[240:241]
	v_pk_mul_f32 v[84:85], v[84:85], v[242:243]
	v_pk_mul_f32 v[86:87], v[86:87], v[244:245]
	v_pk_mul_f32 v[80:81], v[80:81], v[246:247]
	v_pk_mul_f32 v[82:83], v[82:83], v[150:151]
	v_cvt_pk_bf16_f32 v186, v92, v93
	v_cvt_pk_bf16_f32 v187, v94, v95
	v_cvt_pk_bf16_f32 v188, v88, v89
	v_cvt_pk_bf16_f32 v189, v90, v91
	v_cvt_pk_bf16_f32 v190, v84, v85
	v_cvt_pk_bf16_f32 v191, v86, v87
	v_cvt_pk_bf16_f32 v192, v80, v81
	v_cvt_pk_bf16_f32 v193, v82, v83
	global_store_dwordx4 v149, v[186:189], s[82:83]
	global_store_dwordx4 v149, v[190:193], s[82:83] offset:256
	s_waitcnt vmcnt(14)
; __device__ __forceinline__ unsigned pk_bf16(float lo, float hi) { const f32x2 v = {lo, hi}; const bf16x2_t b = __builtin_convertvector(v, bf16x2_t); return __builtin_bit_cast(unsigned, b); }
; __device__ __forceinline__ float lo_bf(unsigned w) { return __uint_as_float(w << 16); }
; __device__ __forceinline__ float hi_bf(unsigned w) { return __uint_as_float(w & 0xffff0000u); }
;     __device__ __forceinline__ void operator()(const f32x4 (&acc)[2][2][4][2], const Unit& u, int wr, int wc, int fr, int fq) const {
;         const int row0 = u.pm * BM + wr * 64 + fr, col0 = u.pn * BM + wc * 32 + 8 * fq;
; #pragma unroll
;         for (int ai = 0; ai < 2; ++ai)
; #pragma unroll
;             for (int m = 0; m < 4; ++m) {
;                 const size_t off = (size_t)(row0 + ai * HALF + m * 16) * D + col0;
; #pragma unroll
;                 for (int bj = 0; bj < 2; ++bj) {
;                     const u32x4 gw = *(const u32x4*)(gate + off + bj * HALF);
;                     const f32x4 v0 = acc[ai][bj][m][0], v1 = acc[ai][bj][m][1];
;                     float r[8];
;                     r[0] = lo_bf(gw.x) * v0[0]; r[1] = hi_bf(gw.x) * v0[1]; r[2] = lo_bf(gw.y) * v0[2]; r[3] = hi_bf(gw.y) * v0[3];
;                     r[4] = lo_bf(gw.z) * v1[0]; r[5] = hi_bf(gw.z) * v1[1]; r[6] = lo_bf(gw.w) * v1[2]; r[7] = hi_bf(gw.w) * v1[3];
;                     if (ADD) {
;                         const u32x4 aw = *(const u32x4*)(add + off + bj * HALF);
;                         r[0] += lo_bf(aw.x); r[1] += hi_bf(aw.x); r[2] += lo_bf(aw.y); r[3] += hi_bf(aw.y);
;                         r[4] += lo_bf(aw.z); r[5] += hi_bf(aw.z); r[6] += lo_bf(aw.w); r[7] += hi_bf(aw.w);
;                     }
;                     u32x4 w; w.x = pk_bf16(r[0], r[1]); w.y = pk_bf16(r[2], r[3]); w.z = pk_bf16(r[4], r[5]); w.w = pk_bf16(r[6], r[7]);
;                     *(u32x4*)(out + off + bj * HALF) = w;
;                 }
;                 asm volatile("" ::: "memory");
;             }
	v_lshlrev_b32_e32 v234, 16, v194
	v_and_b32_e32 v235, 0xffff0000, v194
	v_lshlrev_b32_e32 v236, 16, v195
	v_and_b32_e32 v237, 0xffff0000, v195
	v_lshlrev_b32_e32 v238, 16, v196
	v_and_b32_e32 v239, 0xffff0000, v196
	v_lshlrev_b32_e32 v240, 16, v197
	v_and_b32_e32 v241, 0xffff0000, v197
	v_lshlrev_b32_e32 v242, 16, v198
	v_and_b32_e32 v243, 0xffff0000, v198
	v_lshlrev_b32_e32 v244, 16, v199
	v_and_b32_e32 v245, 0xffff0000, v199
	v_lshlrev_b32_e32 v246, 16, v200
	v_and_b32_e32 v247, 0xffff0000, v200
	v_lshlrev_b32_e32 v150, 16, v201
	v_and_b32_e32 v151, 0xffff0000, v201
	v_pk_mul_f32 v[76:77], v[76:77], v[234:235]
	v_pk_mul_f32 v[78:79], v[78:79], v[236:237]
	v_pk_mul_f32 v[72:73], v[72:73], v[238:239]
	v_pk_mul_f32 v[74:75], v[74:75], v[240:241]
	v_pk_mul_f32 v[68:69], v[68:69], v[242:243]
	v_pk_mul_f32 v[70:71], v[70:71], v[244:245]
	v_pk_mul_f32 v[64:65], v[64:65], v[246:247]
	v_pk_mul_f32 v[66:67], v[66:67], v[150:151]
	v_cvt_pk_bf16_f32 v194, v76, v77
	v_cvt_pk_bf16_f32 v195, v78, v79
	v_cvt_pk_bf16_f32 v196, v72, v73
	v_cvt_pk_bf16_f32 v197, v74, v75
	v_cvt_pk_bf16_f32 v198, v68, v69
	v_cvt_pk_bf16_f32 v199, v70, v71
	v_cvt_pk_bf16_f32 v200, v64, v65
	v_cvt_pk_bf16_f32 v201, v66, v67
	global_store_dwordx4 v149, v[194:197], s[84:85]
	global_store_dwordx4 v149, v[198:201], s[84:85] offset:256
	s_waitcnt vmcnt(14)
	v_lshlrev_b32_e32 v234, 16, v202
	v_and_b32_e32 v235, 0xffff0000, v202
	v_lshlrev_b32_e32 v236, 16, v203
	v_and_b32_e32 v237, 0xffff0000, v203
	v_lshlrev_b32_e32 v238, 16, v204
	v_and_b32_e32 v239, 0xffff0000, v204
	v_lshlrev_b32_e32 v240, 16, v205
	v_and_b32_e32 v241, 0xffff0000, v205
	v_lshlrev_b32_e32 v242, 16, v206
	v_and_b32_e32 v243, 0xffff0000, v206
	v_lshlrev_b32_e32 v244, 16, v207
	v_and_b32_e32 v245, 0xffff0000, v207
	v_lshlrev_b32_e32 v246, 16, v208
	v_and_b32_e32 v247, 0xffff0000, v208
	v_lshlrev_b32_e32 v150, 16, v209
	v_and_b32_e32 v151, 0xffff0000, v209
	v_pk_mul_f32 v[60:61], v[60:61], v[234:235]
	v_pk_mul_f32 v[62:63], v[62:63], v[236:237]
	v_pk_mul_f32 v[56:57], v[56:57], v[238:239]
	v_pk_mul_f32 v[58:59], v[58:59], v[240:241]
	v_pk_mul_f32 v[52:53], v[52:53], v[242:243]
	v_pk_mul_f32 v[54:55], v[54:55], v[244:245]
	v_pk_mul_f32 v[48:49], v[48:49], v[246:247]
	v_pk_mul_f32 v[50:51], v[50:51], v[150:151]
	v_cvt_pk_bf16_f32 v202, v60, v61
	v_cvt_pk_bf16_f32 v203, v62, v63
	v_cvt_pk_bf16_f32 v204, v56, v57
	v_cvt_pk_bf16_f32 v205, v58, v59
	v_cvt_pk_bf16_f32 v206, v52, v53
	v_cvt_pk_bf16_f32 v207, v54, v55
	v_cvt_pk_bf16_f32 v208, v48, v49
	v_cvt_pk_bf16_f32 v209, v50, v51
	global_store_dwordx4 v149, v[202:205], s[86:87]
	global_store_dwordx4 v149, v[206:209], s[86:87] offset:256
	s_waitcnt vmcnt(14)
	v_lshlrev_b32_e32 v234, 16, v210
	v_and_b32_e32 v235, 0xffff0000, v210
	v_lshlrev_b32_e32 v236, 16, v211
	v_and_b32_e32 v237, 0xffff0000, v211
	v_lshlrev_b32_e32 v238, 16, v212
	v_and_b32_e32 v239, 0xffff0000, v212
	v_lshlrev_b32_e32 v240, 16, v213
	v_and_b32_e32 v241, 0xffff0000, v213
	v_lshlrev_b32_e32 v242, 16, v214
	v_and_b32_e32 v243, 0xffff0000, v214
	v_lshlrev_b32_e32 v244, 16, v215
	v_and_b32_e32 v245, 0xffff0000, v215
	v_lshlrev_b32_e32 v246, 16, v216
	v_and_b32_e32 v247, 0xffff0000, v216
	v_lshlrev_b32_e32 v150, 16, v217
	v_and_b32_e32 v151, 0xffff0000, v217
	v_pk_mul_f32 v[44:45], v[44:45], v[234:235]
	v_pk_mul_f32 v[46:47], v[46:47], v[236:237]
	v_pk_mul_f32 v[40:41], v[40:41], v[238:239]
	v_pk_mul_f32 v[42:43], v[42:43], v[240:241]
	v_pk_mul_f32 v[36:37], v[36:37], v[242:243]
	v_pk_mul_f32 v[38:39], v[38:39], v[244:245]
	v_pk_mul_f32 v[32:33], v[32:33], v[246:247]
	v_pk_mul_f32 v[34:35], v[34:35], v[150:151]
	v_cvt_pk_bf16_f32 v210, v44, v45
	v_cvt_pk_bf16_f32 v211, v46, v47
	v_cvt_pk_bf16_f32 v212, v40, v41
	v_cvt_pk_bf16_f32 v213, v42, v43
	v_cvt_pk_bf16_f32 v214, v36, v37
	v_cvt_pk_bf16_f32 v215, v38, v39
	v_cvt_pk_bf16_f32 v216, v32, v33
	v_cvt_pk_bf16_f32 v217, v34, v35
	global_store_dwordx4 v149, v[210:213], s[88:89]
	global_store_dwordx4 v149, v[214:217], s[88:89] offset:256
	s_waitcnt vmcnt(14)
	v_lshlrev_b32_e32 v234, 16, v218
	v_and_b32_e32 v235, 0xffff0000, v218
	v_lshlrev_b32_e32 v236, 16, v219
	v_and_b32_e32 v237, 0xffff0000, v219
	v_lshlrev_b32_e32 v238, 16, v220
	v_and_b32_e32 v239, 0xffff0000, v220
	v_lshlrev_b32_e32 v240, 16, v221
	v_and_b32_e32 v241, 0xffff0000, v221
	v_lshlrev_b32_e32 v242, 16, v222
	v_and_b32_e32 v243, 0xffff0000, v222
	v_lshlrev_b32_e32 v244, 16, v223
	v_and_b32_e32 v245, 0xffff0000, v223
	v_lshlrev_b32_e32 v246, 16, v224
	v_and_b32_e32 v247, 0xffff0000, v224
	v_lshlrev_b32_e32 v150, 16, v225
	v_and_b32_e32 v151, 0xffff0000, v225
	v_pk_mul_f32 v[28:29], v[28:29], v[234:235]
	v_pk_mul_f32 v[30:31], v[30:31], v[236:237]
	v_pk_mul_f32 v[24:25], v[24:25], v[238:239]
	v_pk_mul_f32 v[26:27], v[26:27], v[240:241]
	v_pk_mul_f32 v[20:21], v[20:21], v[242:243]
	v_pk_mul_f32 v[22:23], v[22:23], v[244:245]
	v_pk_mul_f32 v[16:17], v[16:17], v[246:247]
	v_pk_mul_f32 v[18:19], v[18:19], v[150:151]
	v_cvt_pk_bf16_f32 v218, v28, v29
	v_cvt_pk_bf16_f32 v219, v30, v31
	v_cvt_pk_bf16_f32 v220, v24, v25
	v_cvt_pk_bf16_f32 v221, v26, v27
	v_cvt_pk_bf16_f32 v222, v20, v21
	v_cvt_pk_bf16_f32 v223, v22, v23
	v_cvt_pk_bf16_f32 v224, v16, v17
	v_cvt_pk_bf16_f32 v225, v18, v19
	global_store_dwordx4 v149, v[218:221], s[68:69]
	global_store_dwordx4 v149, v[222:225], s[68:69] offset:256
	s_waitcnt vmcnt(14)
	v_lshlrev_b32_e32 v234, 16, v226
	v_and_b32_e32 v235, 0xffff0000, v226
	v_lshlrev_b32_e32 v236, 16, v227
	v_and_b32_e32 v237, 0xffff0000, v227
	v_lshlrev_b32_e32 v238, 16, v228
	v_and_b32_e32 v239, 0xffff0000, v228
	v_lshlrev_b32_e32 v240, 16, v229
	v_and_b32_e32 v241, 0xffff0000, v229
	v_lshlrev_b32_e32 v242, 16, v230
	v_and_b32_e32 v243, 0xffff0000, v230
	v_lshlrev_b32_e32 v244, 16, v231
	v_and_b32_e32 v245, 0xffff0000, v231
	v_lshlrev_b32_e32 v246, 16, v232
	v_and_b32_e32 v247, 0xffff0000, v232
	v_lshlrev_b32_e32 v150, 16, v233
	v_and_b32_e32 v151, 0xffff0000, v233
	v_pk_mul_f32 v[12:13], v[12:13], v[234:235]
	v_pk_mul_f32 v[14:15], v[14:15], v[236:237]
	v_pk_mul_f32 v[8:9], v[8:9], v[238:239]
	v_pk_mul_f32 v[10:11], v[10:11], v[240:241]
	v_pk_mul_f32 v[4:5], v[4:5], v[242:243]
	v_pk_mul_f32 v[6:7], v[6:7], v[244:245]
	v_pk_mul_f32 v[0:1], v[0:1], v[246:247]
	v_pk_mul_f32 v[2:3], v[2:3], v[150:151]
	v_cvt_pk_bf16_f32 v226, v12, v13
	v_cvt_pk_bf16_f32 v227, v14, v15
	v_cvt_pk_bf16_f32 v228, v8, v9
	v_cvt_pk_bf16_f32 v229, v10, v11
	v_cvt_pk_bf16_f32 v230, v4, v5
	v_cvt_pk_bf16_f32 v231, v6, v7
	v_cvt_pk_bf16_f32 v232, v0, v1
	v_cvt_pk_bf16_f32 v233, v2, v3
	global_store_dwordx4 v149, v[226:229], s[70:71]
	global_store_dwordx4 v149, v[230:233], s[70:71] offset:256
	s_andn2_b64 vcc, exec, s[0:1]
	s_mov_b64 s[0:1], -1
	s_cbranch_vccnz .LBB0_868
	s_andn2_b64 vcc, exec, s[8:9]
	s_cbranch_vccnz .LBB0_867
	s_barrier
	s_branch .LBB0_867
